# QK-norm phase: bf16 packing by v_cvt_pk_bf16_f32 instead of the 6-instruction round-to-nearest-even bit trick (10 per row)
# baseline (speedup 1.0000x reference)
; __device__ __forceinline__ float bf_lo(unsigned w) { return __uint_as_float(w << 16); }
; __device__ __forceinline__ float bf_hi(unsigned w) { return __uint_as_float(w & 0xffff0000u); }
; __device__ __forceinline__ unsigned f2bf(float f) { unsigned u = __builtin_bit_cast(unsigned, f); return (u + 0x7fffu + ((u >> 16) & 1u)) >> 16; }
; __device__ __forceinline__ unsigned pk2(float lo, float hi) { return f2bf(lo) | (f2bf(hi) << 16); }
; __global__ void __launch_bounds__(NWAVES * 64) fwd_kernel(Args args) {
;     ...
;                 bf16_t* base = QKV + (size_t)r * NIN;
;                 unsigned wv[10];
; #pragma unroll
;                 for (int hh = 0; hh < 10; ++hh) wv[hh] = *((const unsigned*)(base + (hh < 8 ? 3072 + hh * 128 : 4096 + (hh - 8) * 128)) + lane);
;                 const float gq0 = qkg[2 * lane], gq1 = qkg[2 * lane + 1], gk0 = qkg[128 + 2 * lane], gk1 = qkg[128 + 2 * lane + 1];
; #pragma unroll
;                 for (int hh = 0; hh < 10; ++hh) { const int off = hh < 8 ? 3072 + hh * 128 : 4096 + (hh - 8) * 128; const float qs = hh < 8 ? QSCALE_B : 1.f;
;                     const float x0 = pg8::bf_lo(wv[hh]), x1 = pg8::bf_hi(wv[hh]);
;                     const float s2 = wave_sum(x0 * x0 + x1 * x1); const float rn = __builtin_amdgcn_rsqf(s2 * (1.0f / 128.0f) + EPS);
;                     const float y0 = x0 * rn * (hh < 8 ? gq0 : gk0), y1 = x1 * rn * (hh < 8 ? gq1 : gk1);
;                     *((unsigned*)(base + off) + lane) = pk2((y0 * c - y1 * sn) * qs, (y0 * sn + y1 * c) * qs); }
.LBB0_414:
	flat_load_dword v17, v[6:7]
	flat_load_dword v18, v[6:7] offset:256
	flat_load_dword v19, v[6:7] offset:512
	flat_load_dword v16, v[6:7] offset:768
	flat_load_dword v15, v[6:7] offset:1024
	flat_load_dword v14, v[6:7] offset:1280
	flat_load_dword v13, v[6:7] offset:1536
	flat_load_dword v12, v[6:7] offset:1792
	flat_load_dword v11, v[6:7] offset:2048
	flat_load_dword v10, v[6:7] offset:2304
	s_add_i32 s4, s4, s47
	s_cmpk_gt_i32 s4, 0x604f
	s_waitcnt vmcnt(0) lgkmcnt(0)
	v_lshlrev_b32_e32 v20, 16, v17
	v_and_b32_e32 v17, 0xffff0000, v17
	v_mul_f32_e32 v21, v17, v17
	v_fmac_f32_e32 v21, v20, v20
	s_nop 1
	v_add_f32_dpp v21, v21, v21 quad_perm:[1,0,3,2] row_mask:0xf bank_mask:0xf
	s_nop 1
	v_add_f32_dpp v21, v21, v21 quad_perm:[2,3,0,1] row_mask:0xf bank_mask:0xf
	s_nop 1
	v_add_f32_dpp v21, v21, v21 row_half_mirror row_mask:0xf bank_mask:0xf
	s_nop 1
	v_add_f32_dpp v21, v21, v21 row_mirror row_mask:0xf bank_mask:0xf
	v_mov_b32_e32 v22, v21
	s_nop 1
	v_permlane16_swap_b32_e32 v21, v22
	s_waitcnt lgkmcnt(0)
	v_add_f32_e32 v21, v21, v22
	v_mov_b32_e32 v22, v21
	s_nop 1
	v_permlane32_swap_b32_e32 v21, v22
	v_add_f32_e32 v21, v21, v22
	v_fmamk_f32 v21, v21, 0x3c000000, v215
	v_rsq_f32_e32 v21, v21
	s_nop 0
	v_mul_f32_e32 v17, v21, v17
	v_mul_f32_e32 v20, v21, v20
	v_mul_f32_e32 v17, v3, v17
	v_mul_f32_e32 v20, v2, v20
	v_mul_f32_e32 v21, v0, v17
	v_fma_f32 v21, v9, v20, -v21
	v_mul_f32_e32 v17, v9, v17
	v_mul_f32_e32 v21, 0x3e0293ee, v21
	v_fmac_f32_e32 v17, v0, v20
	v_mul_f32_e32 v17, 0x3e0293ee, v17
	v_cvt_pk_bf16_f32 v17, v21, v17
	flat_store_dword v[6:7], v17
	v_lshlrev_b32_e32 v17, 16, v18
	v_and_b32_e32 v18, 0xffff0000, v18
	v_mul_f32_e32 v20, v18, v18
	v_fmac_f32_e32 v20, v17, v17
	s_nop 1
	v_add_f32_dpp v20, v20, v20 quad_perm:[1,0,3,2] row_mask:0xf bank_mask:0xf
	s_nop 1
	v_add_f32_dpp v20, v20, v20 quad_perm:[2,3,0,1] row_mask:0xf bank_mask:0xf
	s_nop 1
	v_add_f32_dpp v20, v20, v20 row_half_mirror row_mask:0xf bank_mask:0xf
	s_nop 1
	v_add_f32_dpp v20, v20, v20 row_mirror row_mask:0xf bank_mask:0xf
	v_mov_b32_e32 v21, v20
	s_nop 1
	v_permlane16_swap_b32_e32 v20, v21
	s_waitcnt lgkmcnt(0)
	v_add_f32_e32 v20, v20, v21
	v_mov_b32_e32 v21, v20
	s_nop 1
	v_permlane32_swap_b32_e32 v20, v21
	v_add_f32_e32 v20, v20, v21
	v_fmamk_f32 v20, v20, 0x3c000000, v215
	v_rsq_f32_e32 v20, v20
	s_nop 0
	v_mul_f32_e32 v18, v20, v18
	v_mul_f32_e32 v17, v20, v17
	v_mul_f32_e32 v18, v3, v18
	v_mul_f32_e32 v17, v2, v17
	v_mul_f32_e32 v20, v0, v18
	v_fma_f32 v20, v9, v17, -v20
	v_mul_f32_e32 v18, v9, v18
	v_mul_f32_e32 v20, 0x3e0293ee, v20
	v_fmac_f32_e32 v18, v0, v17
	v_mul_f32_e32 v17, 0x3e0293ee, v18
	v_cvt_pk_bf16_f32 v17, v20, v17
	v_and_b32_e32 v18, 0xffff0000, v19
	flat_store_dword v[6:7], v17 offset:256
	v_lshlrev_b32_e32 v17, 16, v19
	v_mul_f32_e32 v19, v18, v18
	v_fmac_f32_e32 v19, v17, v17
	s_nop 1
	v_add_f32_dpp v19, v19, v19 quad_perm:[1,0,3,2] row_mask:0xf bank_mask:0xf
	s_nop 1
	v_add_f32_dpp v19, v19, v19 quad_perm:[2,3,0,1] row_mask:0xf bank_mask:0xf
	s_nop 1
	v_add_f32_dpp v19, v19, v19 row_half_mirror row_mask:0xf bank_mask:0xf
	s_nop 1
	v_add_f32_dpp v19, v19, v19 row_mirror row_mask:0xf bank_mask:0xf
	v_mov_b32_e32 v20, v19
	s_nop 1
	v_permlane16_swap_b32_e32 v19, v20
	s_waitcnt lgkmcnt(0)
	v_add_f32_e32 v19, v19, v20
	v_mov_b32_e32 v20, v19
	s_nop 1
	v_permlane32_swap_b32_e32 v19, v20
	v_add_f32_e32 v19, v19, v20
	v_fmamk_f32 v19, v19, 0x3c000000, v215
	v_rsq_f32_e32 v19, v19
	s_nop 0
	v_mul_f32_e32 v18, v19, v18
	v_mul_f32_e32 v17, v19, v17
	v_mul_f32_e32 v18, v3, v18
	v_mul_f32_e32 v17, v2, v17
	v_mul_f32_e32 v19, v0, v18
	v_fma_f32 v19, v9, v17, -v19
	v_mul_f32_e32 v18, v9, v18
	v_mul_f32_e32 v19, 0x3e0293ee, v19
	v_fmac_f32_e32 v18, v0, v17
	v_mul_f32_e32 v17, 0x3e0293ee, v18
	v_cvt_pk_bf16_f32 v17, v19, v17
	flat_store_dword v[6:7], v17 offset:512
	v_lshlrev_b32_e32 v17, 16, v16
	v_and_b32_e32 v16, 0xffff0000, v16
	v_mul_f32_e32 v18, v16, v16
	v_fmac_f32_e32 v18, v17, v17
	s_nop 1
	v_add_f32_dpp v18, v18, v18 quad_perm:[1,0,3,2] row_mask:0xf bank_mask:0xf
	s_nop 1
	v_add_f32_dpp v18, v18, v18 quad_perm:[2,3,0,1] row_mask:0xf bank_mask:0xf
	s_nop 1
	v_add_f32_dpp v18, v18, v18 row_half_mirror row_mask:0xf bank_mask:0xf
	s_nop 1
	v_add_f32_dpp v18, v18, v18 row_mirror row_mask:0xf bank_mask:0xf
	v_mov_b32_e32 v19, v18
	s_nop 1
	v_permlane16_swap_b32_e32 v18, v19
	s_waitcnt lgkmcnt(0)
	v_add_f32_e32 v18, v18, v19
	v_mov_b32_e32 v19, v18
	s_nop 1
	v_permlane32_swap_b32_e32 v18, v19
	v_add_f32_e32 v18, v18, v19
	v_fmamk_f32 v18, v18, 0x3c000000, v215
	v_rsq_f32_e32 v18, v18
	s_nop 0
	v_mul_f32_e32 v16, v18, v16
	v_mul_f32_e32 v17, v18, v17
	v_mul_f32_e32 v16, v3, v16
	v_mul_f32_e32 v17, v2, v17
	v_mul_f32_e32 v18, v0, v16
	v_fma_f32 v18, v9, v17, -v18
	v_mul_f32_e32 v16, v9, v16
	v_mul_f32_e32 v18, 0x3e0293ee, v18
	v_fmac_f32_e32 v16, v0, v17
	v_mul_f32_e32 v16, 0x3e0293ee, v16
	v_cvt_pk_bf16_f32 v16, v18, v16
	flat_store_dword v[6:7], v16 offset:768
	v_lshlrev_b32_e32 v16, 16, v15
	v_and_b32_e32 v15, 0xffff0000, v15
	v_mul_f32_e32 v17, v15, v15
	v_fmac_f32_e32 v17, v16, v16
	s_nop 1
	v_add_f32_dpp v17, v17, v17 quad_perm:[1,0,3,2] row_mask:0xf bank_mask:0xf
	s_nop 1
	v_add_f32_dpp v17, v17, v17 quad_perm:[2,3,0,1] row_mask:0xf bank_mask:0xf
	s_nop 1
	v_add_f32_dpp v17, v17, v17 row_half_mirror row_mask:0xf bank_mask:0xf
	s_nop 1
	v_add_f32_dpp v17, v17, v17 row_mirror row_mask:0xf bank_mask:0xf
	v_mov_b32_e32 v18, v17
	s_nop 1
	v_permlane16_swap_b32_e32 v17, v18
	s_waitcnt lgkmcnt(0)
; __device__ __forceinline__ float bf_lo(unsigned w) { return __uint_as_float(w << 16); }
; __device__ __forceinline__ float bf_hi(unsigned w) { return __uint_as_float(w & 0xffff0000u); }
; __device__ __forceinline__ unsigned f2bf(float f) { unsigned u = __builtin_bit_cast(unsigned, f); return (u + 0x7fffu + ((u >> 16) & 1u)) >> 16; }
; __device__ __forceinline__ unsigned pk2(float lo, float hi) { return f2bf(lo) | (f2bf(hi) << 16); }
; __global__ void __launch_bounds__(NWAVES * 64) fwd_kernel(Args args) {
;     ...
;                 bf16_t* base = QKV + (size_t)r * NIN;
;                 unsigned wv[10];
; #pragma unroll
;                 for (int hh = 0; hh < 10; ++hh) wv[hh] = *((const unsigned*)(base + (hh < 8 ? 3072 + hh * 128 : 4096 + (hh - 8) * 128)) + lane);
;                 const float gq0 = qkg[2 * lane], gq1 = qkg[2 * lane + 1], gk0 = qkg[128 + 2 * lane], gk1 = qkg[128 + 2 * lane + 1];
; #pragma unroll
;                 for (int hh = 0; hh < 10; ++hh) { const int off = hh < 8 ? 3072 + hh * 128 : 4096 + (hh - 8) * 128; const float qs = hh < 8 ? QSCALE_B : 1.f;
;                     const float x0 = pg8::bf_lo(wv[hh]), x1 = pg8::bf_hi(wv[hh]);
;                     const float s2 = wave_sum(x0 * x0 + x1 * x1); const float rn = __builtin_amdgcn_rsqf(s2 * (1.0f / 128.0f) + EPS);
;                     const float y0 = x0 * rn * (hh < 8 ? gq0 : gk0), y1 = x1 * rn * (hh < 8 ? gq1 : gk1);
;                     *((unsigned*)(base + off) + lane) = pk2((y0 * c - y1 * sn) * qs, (y0 * sn + y1 * c) * qs); }
	v_add_f32_e32 v17, v17, v18
	v_mov_b32_e32 v18, v17
	s_nop 1
	v_permlane32_swap_b32_e32 v17, v18
	v_add_f32_e32 v17, v17, v18
	v_fmamk_f32 v17, v17, 0x3c000000, v215
	v_rsq_f32_e32 v17, v17
	s_nop 0
	v_mul_f32_e32 v15, v17, v15
	v_mul_f32_e32 v16, v17, v16
	v_mul_f32_e32 v15, v3, v15
	v_mul_f32_e32 v16, v2, v16
	v_mul_f32_e32 v17, v0, v15
	v_fma_f32 v17, v9, v16, -v17
	v_mul_f32_e32 v15, v9, v15
	v_mul_f32_e32 v17, 0x3e0293ee, v17
	v_fmac_f32_e32 v15, v0, v16
	v_mul_f32_e32 v15, 0x3e0293ee, v15
	v_cvt_pk_bf16_f32 v15, v17, v15
	flat_store_dword v[6:7], v15 offset:1024
	v_lshlrev_b32_e32 v15, 16, v14
	v_and_b32_e32 v14, 0xffff0000, v14
	v_mul_f32_e32 v16, v14, v14
	v_fmac_f32_e32 v16, v15, v15
	s_nop 1
	v_add_f32_dpp v16, v16, v16 quad_perm:[1,0,3,2] row_mask:0xf bank_mask:0xf
	s_nop 1
	v_add_f32_dpp v16, v16, v16 quad_perm:[2,3,0,1] row_mask:0xf bank_mask:0xf
	s_nop 1
	v_add_f32_dpp v16, v16, v16 row_half_mirror row_mask:0xf bank_mask:0xf
	s_nop 1
	v_add_f32_dpp v16, v16, v16 row_mirror row_mask:0xf bank_mask:0xf
	v_mov_b32_e32 v17, v16
	s_nop 1
	v_permlane16_swap_b32_e32 v16, v17
	s_waitcnt lgkmcnt(0)
	v_add_f32_e32 v16, v16, v17
	v_mov_b32_e32 v17, v16
	s_nop 1
	v_permlane32_swap_b32_e32 v16, v17
	v_add_f32_e32 v16, v16, v17
	v_fmamk_f32 v16, v16, 0x3c000000, v215
	v_rsq_f32_e32 v16, v16
	s_nop 0
	v_mul_f32_e32 v14, v16, v14
	v_mul_f32_e32 v15, v16, v15
	v_mul_f32_e32 v14, v3, v14
	v_mul_f32_e32 v15, v2, v15
	v_mul_f32_e32 v16, v0, v14
	v_fma_f32 v16, v9, v15, -v16
	v_mul_f32_e32 v14, v9, v14
	v_mul_f32_e32 v16, 0x3e0293ee, v16
	v_fmac_f32_e32 v14, v0, v15
	v_mul_f32_e32 v14, 0x3e0293ee, v14
	v_cvt_pk_bf16_f32 v14, v16, v14
	flat_store_dword v[6:7], v14 offset:1280
	v_lshlrev_b32_e32 v14, 16, v13
	v_and_b32_e32 v13, 0xffff0000, v13
	v_mul_f32_e32 v15, v13, v13
	v_fmac_f32_e32 v15, v14, v14
	s_nop 1
	v_add_f32_dpp v15, v15, v15 quad_perm:[1,0,3,2] row_mask:0xf bank_mask:0xf
	s_nop 1
	v_add_f32_dpp v15, v15, v15 quad_perm:[2,3,0,1] row_mask:0xf bank_mask:0xf
	s_nop 1
	v_add_f32_dpp v15, v15, v15 row_half_mirror row_mask:0xf bank_mask:0xf
	s_nop 1
	v_add_f32_dpp v15, v15, v15 row_mirror row_mask:0xf bank_mask:0xf
	v_mov_b32_e32 v16, v15
	s_nop 1
	v_permlane16_swap_b32_e32 v15, v16
	s_waitcnt lgkmcnt(0)
	v_add_f32_e32 v15, v15, v16
	v_mov_b32_e32 v16, v15
	s_nop 1
	v_permlane32_swap_b32_e32 v15, v16
	v_add_f32_e32 v15, v15, v16
	v_fmamk_f32 v15, v15, 0x3c000000, v215
	v_rsq_f32_e32 v15, v15
	s_nop 0
	v_mul_f32_e32 v13, v15, v13
	v_mul_f32_e32 v14, v15, v14
	v_mul_f32_e32 v13, v3, v13
	v_mul_f32_e32 v14, v2, v14
	v_mul_f32_e32 v15, v0, v13
	v_fma_f32 v15, v9, v14, -v15
	v_mul_f32_e32 v13, v9, v13
	v_mul_f32_e32 v15, 0x3e0293ee, v15
	v_fmac_f32_e32 v13, v0, v14
	v_mul_f32_e32 v13, 0x3e0293ee, v13
	v_cvt_pk_bf16_f32 v13, v15, v13
	flat_store_dword v[6:7], v13 offset:1536
	v_lshlrev_b32_e32 v13, 16, v12
	v_and_b32_e32 v12, 0xffff0000, v12
	v_mul_f32_e32 v14, v12, v12
	v_fmac_f32_e32 v14, v13, v13
	s_nop 1
	v_add_f32_dpp v14, v14, v14 quad_perm:[1,0,3,2] row_mask:0xf bank_mask:0xf
	s_nop 1
	v_add_f32_dpp v14, v14, v14 quad_perm:[2,3,0,1] row_mask:0xf bank_mask:0xf
	s_nop 1
	v_add_f32_dpp v14, v14, v14 row_half_mirror row_mask:0xf bank_mask:0xf
	s_nop 1
	v_add_f32_dpp v14, v14, v14 row_mirror row_mask:0xf bank_mask:0xf
	v_mov_b32_e32 v15, v14
	s_nop 1
	v_permlane16_swap_b32_e32 v14, v15
	s_waitcnt lgkmcnt(0)
	v_add_f32_e32 v14, v14, v15
	v_mov_b32_e32 v15, v14
	s_nop 1
	v_permlane32_swap_b32_e32 v14, v15
	v_add_f32_e32 v14, v14, v15
	v_fmamk_f32 v14, v14, 0x3c000000, v215
	v_rsq_f32_e32 v14, v14
	s_nop 0
	v_mul_f32_e32 v12, v14, v12
	v_mul_f32_e32 v13, v14, v13
	v_mul_f32_e32 v12, v3, v12
	v_mul_f32_e32 v13, v2, v13
	v_mul_f32_e32 v14, v0, v12
	v_fma_f32 v14, v9, v13, -v14
	v_mul_f32_e32 v12, v9, v12
	v_mul_f32_e32 v14, 0x3e0293ee, v14
	v_fmac_f32_e32 v12, v0, v13
	v_mul_f32_e32 v12, 0x3e0293ee, v12
	v_cvt_pk_bf16_f32 v12, v14, v12
	flat_store_dword v[6:7], v12 offset:1792
	v_lshlrev_b32_e32 v12, 16, v11
	v_and_b32_e32 v11, 0xffff0000, v11
	v_mul_f32_e32 v13, v11, v11
	v_fmac_f32_e32 v13, v12, v12
	s_nop 1
	v_add_f32_dpp v13, v13, v13 quad_perm:[1,0,3,2] row_mask:0xf bank_mask:0xf
	s_nop 1
	v_add_f32_dpp v13, v13, v13 quad_perm:[2,3,0,1] row_mask:0xf bank_mask:0xf
	s_nop 1
	v_add_f32_dpp v13, v13, v13 row_half_mirror row_mask:0xf bank_mask:0xf
	s_nop 1
	v_add_f32_dpp v13, v13, v13 row_mirror row_mask:0xf bank_mask:0xf
	v_mov_b32_e32 v14, v13
	s_nop 1
	v_permlane16_swap_b32_e32 v13, v14
	s_waitcnt lgkmcnt(0)
	v_add_f32_e32 v13, v13, v14
	v_mov_b32_e32 v14, v13
	s_nop 1
	v_permlane32_swap_b32_e32 v13, v14
	v_add_f32_e32 v13, v13, v14
	v_fmamk_f32 v13, v13, 0x3c000000, v215
	v_rsq_f32_e32 v13, v13
	s_nop 0
	v_mul_f32_e32 v11, v13, v11
	v_mul_f32_e32 v12, v13, v12
	v_mul_f32_e32 v11, v5, v11
	v_mul_f32_e32 v12, v4, v12
	v_mul_f32_e32 v13, v0, v11
	v_fma_f32 v13, v9, v12, -v13
	v_mul_f32_e32 v11, v9, v11
	v_fmac_f32_e32 v11, v0, v12
	v_cvt_pk_bf16_f32 v11, v13, v11
	flat_store_dword v[6:7], v11 offset:2048
	v_lshlrev_b32_e32 v11, 16, v10
	v_and_b32_e32 v10, 0xffff0000, v10
	v_mul_f32_e32 v12, v10, v10
	v_fmac_f32_e32 v12, v11, v11
	s_nop 1
	v_add_f32_dpp v12, v12, v12 quad_perm:[1,0,3,2] row_mask:0xf bank_mask:0xf
	s_nop 1
	v_add_f32_dpp v12, v12, v12 quad_perm:[2,3,0,1] row_mask:0xf bank_mask:0xf
	s_nop 1
	v_add_f32_dpp v12, v12, v12 row_half_mirror row_mask:0xf bank_mask:0xf
	s_nop 1
	v_add_f32_dpp v12, v12, v12 row_mirror row_mask:0xf bank_mask:0xf
	v_mov_b32_e32 v13, v12
	s_nop 1
	v_permlane16_swap_b32_e32 v12, v13
	s_waitcnt lgkmcnt(0)
	v_add_f32_e32 v12, v12, v13
	v_mov_b32_e32 v13, v12
	s_nop 1
	v_permlane32_swap_b32_e32 v12, v13
	v_add_f32_e32 v12, v12, v13
	v_fmamk_f32 v12, v12, 0x3c000000, v215
	v_rsq_f32_e32 v12, v12
	s_nop 0
	v_mul_f32_e32 v10, v12, v10
	v_mul_f32_e32 v11, v12, v11
	v_mul_f32_e32 v10, v5, v10
	v_mul_f32_e32 v11, v4, v11
	v_mul_f32_e32 v12, v0, v10
	v_fma_f32 v12, v9, v11, -v12
	v_mul_f32_e32 v9, v9, v10
	v_fmac_f32_e32 v9, v0, v11
	v_cvt_pk_bf16_f32 v0, v12, v9
	flat_store_dword v[6:7], v0 offset:2304
	v_lshl_add_u64 v[6:7], v[6:7], 0, s[0:1]
	s_cbranch_scc1 .LBB0_421
